# v28: v27 + SwiGLU epilogue uses global_store_dwordx4 instead of flat_store_dwordx4 (instruction selection; no LGKM coupling)
# speedup vs baseline: 1.0012x; 1.0012x over previous
; __device__ __forceinline__ unsigned cvtpk(float lo, float hi) { f32x2 v = {lo, hi}; bf16x2_t b = __builtin_convertvector(v, bf16x2_t); return __builtin_bit_cast(unsigned, b); }
; __device__ __forceinline__ float silu_f(float g) { return g * __builtin_amdgcn_rcpf(1.0f + fast_exp2(-g * LOG2E)); }
;     __device__ __forceinline__ void operator()(const f32x4 (&acc)[2][2][4][2], const Unit& u, int wr, int wc, int fr, int fq) const {
;         const int row0 = u.pm * BM + wr * 64 + fr, col0 = u.pn * HALF + wc * 32 + 8 * fq;
; #pragma unroll
;         for (int ai = 0; ai < 2; ++ai)
; #pragma unroll
;             for (int m = 0; m < 4; ++m) { bf16_t* rowp = O + (size_t)(row0 + ai * HALF + m * 16) * DFF + col0;
;                 float r[8];
; #pragma unroll
;                 for (int n = 0; n < 2; ++n)
; #pragma unroll
;                     for (int e = 0; e < 4; ++e) r[n * 4 + e] = silu_f(acc[ai][0][m][n][e]) * acc[ai][1][m][n][e];
;                 u32x4 w; w.x = cvtpk(r[0], r[1]); w.y = cvtpk(r[2], r[3]); w.z = cvtpk(r[4], r[5]); w.w = cvtpk(r[6], r[7]);
;                 *(u32x4*)rowp = w; }
.LBB0_704:
	v_mul_f32_e32 v140, 0xbfb8aa3b, v126
	v_exp_f32_e32 v140, v140
	v_mul_f32_e32 v141, 0xbfb8aa3b, v127
	v_exp_f32_e32 v141, v141
	v_mul_f32_e32 v147, 0xbfb8aa3b, v128
	v_add_f32_e32 v140, 1.0, v140
	v_rcp_f32_e32 v150, v140
	v_add_f32_e32 v140, 1.0, v141
	v_rcp_f32_e32 v151, v140
	v_exp_f32_e32 v147, v147
	v_lshl_or_b32 v148, s46, 7, v144
	v_lshl_add_u32 v146, s47, 8, v142
	v_pk_mul_f32 v[126:127], v[126:127], v[150:151]
	v_mul_f32_e32 v150, 0xbfb8aa3b, v129
	v_exp_f32_e32 v150, v150
	v_pk_mul_f32 v[118:119], v[126:127], v[118:119]
	v_add_f32_e32 v126, 1.0, v147
	v_mul_f32_e32 v147, 0xbfb8aa3b, v122
	v_add_f32_e32 v127, 1.0, v150
	v_rcp_f32_e32 v126, v126
	v_rcp_f32_e32 v127, v127
	v_exp_f32_e32 v147, v147
	v_mul_f32_e32 v150, 0xbfb8aa3b, v123
	v_exp_f32_e32 v150, v150
	v_pk_mul_f32 v[126:127], v[128:129], v[126:127]
	v_add_f32_e32 v128, 1.0, v147
	v_mul_f32_e32 v147, 0xbfb8aa3b, v124
	v_add_f32_e32 v129, 1.0, v150
	v_exp_f32_e32 v147, v147
	v_mul_f32_e32 v150, 0xbfb8aa3b, v125
	v_exp_f32_e32 v151, v150
	v_rcp_f32_e32 v128, v128
	v_add_f32_e32 v147, 1.0, v147
	v_rcp_f32_e32 v129, v129
	v_rcp_f32_e32 v150, v147
	v_add_f32_e32 v147, 1.0, v151
	v_rcp_f32_e32 v151, v147
	v_pk_mul_f32 v[122:123], v[122:123], v[128:129]
	v_pk_mul_f32 v[120:121], v[126:127], v[120:121]
	v_pk_mul_f32 v[122:123], v[122:123], v[114:115]
	v_pk_mul_f32 v[114:115], v[124:125], v[150:151]
	v_ashrrev_i32_e32 v149, 31, v148
	v_pk_mul_f32 v[124:125], v[114:115], v[116:117]
	v_cvt_pk_bf16_f32 v117, v120, v121
	v_mul_f32_e32 v120, 0xbfb8aa3b, v110
	v_mul_f32_e32 v121, 0xbfb8aa3b, v111
	v_exp_f32_e32 v120, v120
	v_exp_f32_e32 v121, v121
	v_mov_b64_e32 v[140:141], s[14:15]
	s_movk_i32 s2, 0x80
	v_mad_i64_i32 v[152:153], s[26:27], v146, s2, v[140:141]
	v_and_b32_e32 v114, 15, v142
	v_lshlrev_b32_e32 v115, 6, v114
	v_and_b32_e32 v149, 24, v144
	v_lshl_or_b32 v115, v149, 1, v115
	v_and_b32_e32 v149, 8, v114
	v_lshlrev_b32_e32 v149, 2, v149
	v_xor_b32_e32 v115, v115, v149
	v_lshlrev_b32_e32 v114, 7, v114
	v_sub_u32_e32 v114, v115, v114
	v_bfe_u32 v115, v144, 5, 1
	v_lshl_add_u32 v114, v115, 10, v114
	v_lshrrev_b32_e32 v115, 6, v148
	v_lshl_add_u32 v114, v115, 15, v114
	s_mul_i32 vcc_lo, s47, 0x158000
	v_add_u32_e32 v114, vcc_lo, v114
	v_ashrrev_i32_e32 v115, 31, v114
	v_lshl_add_u64 v[126:127], v[152:153], 0, v[114:115]
	v_cvt_pk_bf16_f32 v116, v118, v119
	v_cvt_pk_bf16_f32 v118, v122, v123
	v_cvt_pk_bf16_f32 v119, v124, v125
	global_store_dwordx4 v[126:127], v[116:119], off
	s_andn2_b64 vcc, exec, s[12:13]
	s_mov_b64 s[12:13], -1
	v_add_f32_e32 v116, 1.0, v120
	v_add_f32_e32 v117, 1.0, v121
	v_rcp_f32_e32 v116, v116
	v_rcp_f32_e32 v117, v117
	v_or_b32_e32 v118, 16, v146
	v_mad_i64_i32 v[118:119], s[26:27], v118, s2, v[140:141]
	v_pk_mul_f32 v[110:111], v[110:111], v[116:117]
	v_mul_f32_e32 v116, 0xbfb8aa3b, v112
	v_mul_f32_e32 v117, 0xbfb8aa3b, v113
	v_exp_f32_e32 v116, v116
	v_exp_f32_e32 v117, v117
	v_pk_mul_f32 v[102:103], v[110:111], v[102:103]
	v_add_f32_e32 v110, 1.0, v116
	v_add_f32_e32 v111, 1.0, v117
	v_mul_f32_e32 v116, 0xbfb8aa3b, v106
	v_mul_f32_e32 v117, 0xbfb8aa3b, v107
	v_rcp_f32_e32 v110, v110
	v_rcp_f32_e32 v111, v111
	v_exp_f32_e32 v116, v116
	v_exp_f32_e32 v117, v117
	v_pk_mul_f32 v[110:111], v[112:113], v[110:111]
	v_add_f32_e32 v112, 1.0, v116
	v_add_f32_e32 v113, 1.0, v117
	v_mul_f32_e32 v116, 0xbfb8aa3b, v108
	v_mul_f32_e32 v117, 0xbfb8aa3b, v109
	v_exp_f32_e32 v116, v116
	v_exp_f32_e32 v117, v117
	v_rcp_f32_e32 v112, v112
	v_rcp_f32_e32 v113, v113
	v_add_f32_e32 v116, 1.0, v116
	v_add_f32_e32 v117, 1.0, v117
	v_rcp_f32_e32 v116, v116
	v_rcp_f32_e32 v117, v117
	v_pk_mul_f32 v[106:107], v[106:107], v[112:113]
	v_pk_mul_f32 v[104:105], v[110:111], v[104:105]
	v_pk_mul_f32 v[106:107], v[106:107], v[98:99]
	v_pk_mul_f32 v[98:99], v[108:109], v[116:117]
	v_lshl_add_u64 v[110:111], v[118:119], 0, v[114:115]
	v_pk_mul_f32 v[108:109], v[98:99], v[100:101]
	v_cvt_pk_bf16_f32 v98, v102, v103
	v_mul_f32_e32 v102, 0xbfb8aa3b, v94
	v_mul_f32_e32 v103, 0xbfb8aa3b, v95
	v_exp_f32_e32 v102, v102
	v_exp_f32_e32 v103, v103
	v_cvt_pk_bf16_f32 v99, v104, v105
	v_cvt_pk_bf16_f32 v100, v106, v107
	v_cvt_pk_bf16_f32 v101, v108, v109
	global_store_dwordx4 v[110:111], v[98:101], off
	s_nop 1
	v_add_f32_e32 v98, 1.0, v102
	v_add_f32_e32 v99, 1.0, v103
	v_rcp_f32_e32 v98, v98
	v_rcp_f32_e32 v99, v99
	v_or_b32_e32 v100, 32, v146
	v_mad_i64_i32 v[100:101], s[26:27], v100, s2, v[140:141]
	v_pk_mul_f32 v[94:95], v[94:95], v[98:99]
	v_mul_f32_e32 v98, 0xbfb8aa3b, v96
	v_mul_f32_e32 v99, 0xbfb8aa3b, v97
	v_exp_f32_e32 v98, v98
	v_exp_f32_e32 v99, v99
	v_pk_mul_f32 v[86:87], v[94:95], v[86:87]
	v_add_f32_e32 v94, 1.0, v98
	v_add_f32_e32 v95, 1.0, v99
	v_mul_f32_e32 v98, 0xbfb8aa3b, v90
	v_mul_f32_e32 v99, 0xbfb8aa3b, v91
	v_rcp_f32_e32 v94, v94
	v_rcp_f32_e32 v95, v95
	v_exp_f32_e32 v98, v98
	v_exp_f32_e32 v99, v99
	v_pk_mul_f32 v[94:95], v[96:97], v[94:95]
	v_add_f32_e32 v96, 1.0, v98
	v_add_f32_e32 v97, 1.0, v99
	v_mul_f32_e32 v98, 0xbfb8aa3b, v92
	v_mul_f32_e32 v99, 0xbfb8aa3b, v93
	v_exp_f32_e32 v98, v98
	v_exp_f32_e32 v99, v99
	v_rcp_f32_e32 v96, v96
	v_rcp_f32_e32 v97, v97
	v_add_f32_e32 v98, 1.0, v98
	v_add_f32_e32 v99, 1.0, v99
	v_rcp_f32_e32 v98, v98
	v_rcp_f32_e32 v99, v99
	v_pk_mul_f32 v[90:91], v[90:91], v[96:97]
	v_pk_mul_f32 v[88:89], v[94:95], v[88:89]
	v_pk_mul_f32 v[90:91], v[90:91], v[82:83]
	v_pk_mul_f32 v[82:83], v[92:93], v[98:99]
	v_lshl_add_u64 v[94:95], v[100:101], 0, v[114:115]
	v_pk_mul_f32 v[92:93], v[82:83], v[84:85]
	v_cvt_pk_bf16_f32 v82, v86, v87
	v_mul_f32_e32 v86, 0xbfb8aa3b, v78
	v_mul_f32_e32 v87, 0xbfb8aa3b, v79
	v_exp_f32_e32 v86, v86
; __device__ __forceinline__ unsigned cvtpk(float lo, float hi) { f32x2 v = {lo, hi}; bf16x2_t b = __builtin_convertvector(v, bf16x2_t); return __builtin_bit_cast(unsigned, b); }
; __device__ __forceinline__ float silu_f(float g) { return g * __builtin_amdgcn_rcpf(1.0f + fast_exp2(-g * LOG2E)); }
;     __device__ __forceinline__ void operator()(const f32x4 (&acc)[2][2][4][2], const Unit& u, int wr, int wc, int fr, int fq) const {
;         const int row0 = u.pm * BM + wr * 64 + fr, col0 = u.pn * HALF + wc * 32 + 8 * fq;
; #pragma unroll
;         for (int ai = 0; ai < 2; ++ai)
; #pragma unroll
;             for (int m = 0; m < 4; ++m) { bf16_t* rowp = O + (size_t)(row0 + ai * HALF + m * 16) * DFF + col0;
;                 float r[8];
; #pragma unroll
;                 for (int n = 0; n < 2; ++n)
; #pragma unroll
;                     for (int e = 0; e < 4; ++e) r[n * 4 + e] = silu_f(acc[ai][0][m][n][e]) * acc[ai][1][m][n][e];
;                 u32x4 w; w.x = cvtpk(r[0], r[1]); w.y = cvtpk(r[2], r[3]); w.z = cvtpk(r[4], r[5]); w.w = cvtpk(r[6], r[7]);
;                 *(u32x4*)rowp = w; }
	v_exp_f32_e32 v87, v87
	v_cvt_pk_bf16_f32 v83, v88, v89
	v_cvt_pk_bf16_f32 v84, v90, v91
	v_cvt_pk_bf16_f32 v85, v92, v93
	global_store_dwordx4 v[94:95], v[82:85], off
	s_nop 1
	v_add_f32_e32 v82, 1.0, v86
	v_add_f32_e32 v83, 1.0, v87
	v_rcp_f32_e32 v82, v82
	v_rcp_f32_e32 v83, v83
	v_or_b32_e32 v84, 48, v146
	v_mad_i64_i32 v[84:85], s[26:27], v84, s2, v[140:141]
	v_pk_mul_f32 v[78:79], v[78:79], v[82:83]
	v_mul_f32_e32 v82, 0xbfb8aa3b, v80
	v_mul_f32_e32 v83, 0xbfb8aa3b, v81
	v_exp_f32_e32 v82, v82
	v_exp_f32_e32 v83, v83
	v_pk_mul_f32 v[70:71], v[78:79], v[70:71]
	v_add_f32_e32 v78, 1.0, v82
	v_add_f32_e32 v79, 1.0, v83
	v_mul_f32_e32 v82, 0xbfb8aa3b, v74
	v_mul_f32_e32 v83, 0xbfb8aa3b, v75
	v_rcp_f32_e32 v78, v78
	v_rcp_f32_e32 v79, v79
	v_exp_f32_e32 v82, v82
	v_exp_f32_e32 v83, v83
	v_pk_mul_f32 v[78:79], v[80:81], v[78:79]
	v_add_f32_e32 v80, 1.0, v82
	v_add_f32_e32 v81, 1.0, v83
	v_mul_f32_e32 v82, 0xbfb8aa3b, v76
	v_mul_f32_e32 v83, 0xbfb8aa3b, v77
	v_exp_f32_e32 v82, v82
	v_exp_f32_e32 v83, v83
	v_rcp_f32_e32 v80, v80
	v_rcp_f32_e32 v81, v81
	v_add_f32_e32 v82, 1.0, v82
	v_add_f32_e32 v83, 1.0, v83
	v_rcp_f32_e32 v82, v82
	v_rcp_f32_e32 v83, v83
	v_pk_mul_f32 v[74:75], v[74:75], v[80:81]
	v_pk_mul_f32 v[72:73], v[78:79], v[72:73]
	v_pk_mul_f32 v[74:75], v[74:75], v[66:67]
	v_pk_mul_f32 v[66:67], v[76:77], v[82:83]
	v_lshl_add_u64 v[78:79], v[84:85], 0, v[114:115]
	v_pk_mul_f32 v[76:77], v[66:67], v[68:69]
	v_cvt_pk_bf16_f32 v66, v70, v71
	v_mul_f32_e32 v70, 0xbfb8aa3b, v62
	v_mul_f32_e32 v71, 0xbfb8aa3b, v63
	v_exp_f32_e32 v70, v70
	v_exp_f32_e32 v71, v71
	v_cvt_pk_bf16_f32 v67, v72, v73
	v_cvt_pk_bf16_f32 v68, v74, v75
	v_cvt_pk_bf16_f32 v69, v76, v77
	global_store_dwordx4 v[78:79], v[66:69], off
	s_nop 1
	v_add_f32_e32 v66, 1.0, v70
	v_add_f32_e32 v67, 1.0, v71
	v_rcp_f32_e32 v66, v66
	v_rcp_f32_e32 v67, v67
	v_add_u32_e32 v68, 0x80, v146
	v_mad_i64_i32 v[68:69], s[26:27], v68, s2, v[140:141]
	v_pk_mul_f32 v[62:63], v[62:63], v[66:67]
	v_mul_f32_e32 v66, 0xbfb8aa3b, v64
	v_mul_f32_e32 v67, 0xbfb8aa3b, v65
	v_exp_f32_e32 v66, v66
	v_exp_f32_e32 v67, v67
	v_pk_mul_f32 v[54:55], v[62:63], v[54:55]
	v_add_f32_e32 v62, 1.0, v66
	v_add_f32_e32 v63, 1.0, v67
	v_mul_f32_e32 v66, 0xbfb8aa3b, v58
	v_mul_f32_e32 v67, 0xbfb8aa3b, v59
	v_rcp_f32_e32 v62, v62
	v_rcp_f32_e32 v63, v63
	v_exp_f32_e32 v66, v66
	v_exp_f32_e32 v67, v67
	v_pk_mul_f32 v[62:63], v[64:65], v[62:63]
	v_add_f32_e32 v64, 1.0, v66
	v_add_f32_e32 v65, 1.0, v67
	v_mul_f32_e32 v66, 0xbfb8aa3b, v60
	v_mul_f32_e32 v67, 0xbfb8aa3b, v61
	v_exp_f32_e32 v66, v66
	v_exp_f32_e32 v67, v67
	v_rcp_f32_e32 v64, v64
	v_rcp_f32_e32 v65, v65
	v_add_f32_e32 v66, 1.0, v66
	v_add_f32_e32 v67, 1.0, v67
	v_rcp_f32_e32 v66, v66
	v_rcp_f32_e32 v67, v67
	v_pk_mul_f32 v[58:59], v[58:59], v[64:65]
	v_pk_mul_f32 v[56:57], v[62:63], v[56:57]
	v_pk_mul_f32 v[58:59], v[58:59], v[50:51]
	v_pk_mul_f32 v[50:51], v[60:61], v[66:67]
	v_lshl_add_u64 v[62:63], v[68:69], 0, v[114:115]
	v_pk_mul_f32 v[60:61], v[50:51], v[52:53]
	v_cvt_pk_bf16_f32 v50, v54, v55
	v_mul_f32_e32 v54, 0xbfb8aa3b, v46
	v_mul_f32_e32 v55, 0xbfb8aa3b, v47
	v_exp_f32_e32 v54, v54
	v_exp_f32_e32 v55, v55
	v_cvt_pk_bf16_f32 v51, v56, v57
	v_cvt_pk_bf16_f32 v52, v58, v59
	v_cvt_pk_bf16_f32 v53, v60, v61
	global_store_dwordx4 v[62:63], v[50:53], off
	s_nop 1
	v_add_f32_e32 v50, 1.0, v54
	v_add_f32_e32 v51, 1.0, v55
	v_rcp_f32_e32 v50, v50
	v_rcp_f32_e32 v51, v51
	v_add_u32_e32 v52, 0x90, v146
	v_mad_i64_i32 v[52:53], s[26:27], v52, s2, v[140:141]
	v_pk_mul_f32 v[46:47], v[46:47], v[50:51]
	v_mul_f32_e32 v50, 0xbfb8aa3b, v48
	v_mul_f32_e32 v51, 0xbfb8aa3b, v49
	v_exp_f32_e32 v50, v50
	v_exp_f32_e32 v51, v51
	v_pk_mul_f32 v[38:39], v[46:47], v[38:39]
	v_add_f32_e32 v46, 1.0, v50
	v_add_f32_e32 v47, 1.0, v51
	v_mul_f32_e32 v50, 0xbfb8aa3b, v42
	v_mul_f32_e32 v51, 0xbfb8aa3b, v43
	v_rcp_f32_e32 v46, v46
	v_rcp_f32_e32 v47, v47
	v_exp_f32_e32 v50, v50
	v_exp_f32_e32 v51, v51
	v_pk_mul_f32 v[46:47], v[48:49], v[46:47]
; __device__ __forceinline__ unsigned cvtpk(float lo, float hi) { f32x2 v = {lo, hi}; bf16x2_t b = __builtin_convertvector(v, bf16x2_t); return __builtin_bit_cast(unsigned, b); }
; __device__ __forceinline__ float silu_f(float g) { return g * __builtin_amdgcn_rcpf(1.0f + fast_exp2(-g * LOG2E)); }
;     __device__ __forceinline__ void operator()(const f32x4 (&acc)[2][2][4][2], const Unit& u, int wr, int wc, int fr, int fq) const {
;         const int row0 = u.pm * BM + wr * 64 + fr, col0 = u.pn * HALF + wc * 32 + 8 * fq;
; #pragma unroll
;         for (int ai = 0; ai < 2; ++ai)
; #pragma unroll
;             for (int m = 0; m < 4; ++m) { bf16_t* rowp = O + (size_t)(row0 + ai * HALF + m * 16) * DFF + col0;
;                 float r[8];
; #pragma unroll
;                 for (int n = 0; n < 2; ++n)
; #pragma unroll
;                     for (int e = 0; e < 4; ++e) r[n * 4 + e] = silu_f(acc[ai][0][m][n][e]) * acc[ai][1][m][n][e];
;                 u32x4 w; w.x = cvtpk(r[0], r[1]); w.y = cvtpk(r[2], r[3]); w.z = cvtpk(r[4], r[5]); w.w = cvtpk(r[6], r[7]);
;                 *(u32x4*)rowp = w; }
	v_add_f32_e32 v48, 1.0, v50
	v_add_f32_e32 v49, 1.0, v51
	v_mul_f32_e32 v50, 0xbfb8aa3b, v44
	v_mul_f32_e32 v51, 0xbfb8aa3b, v45
	v_exp_f32_e32 v50, v50
	v_exp_f32_e32 v51, v51
	v_rcp_f32_e32 v48, v48
	v_rcp_f32_e32 v49, v49
	v_add_f32_e32 v50, 1.0, v50
	v_add_f32_e32 v51, 1.0, v51
	v_rcp_f32_e32 v50, v50
	v_rcp_f32_e32 v51, v51
	v_pk_mul_f32 v[42:43], v[42:43], v[48:49]
	v_pk_mul_f32 v[40:41], v[46:47], v[40:41]
	v_pk_mul_f32 v[42:43], v[42:43], v[34:35]
	v_pk_mul_f32 v[34:35], v[44:45], v[50:51]
	v_lshl_add_u64 v[46:47], v[52:53], 0, v[114:115]
	v_pk_mul_f32 v[44:45], v[34:35], v[36:37]
	v_cvt_pk_bf16_f32 v34, v38, v39
	v_mul_f32_e32 v38, 0xbfb8aa3b, v30
	v_mul_f32_e32 v39, 0xbfb8aa3b, v31
	v_exp_f32_e32 v38, v38
	v_exp_f32_e32 v39, v39
	v_cvt_pk_bf16_f32 v35, v40, v41
	v_cvt_pk_bf16_f32 v36, v42, v43
	v_cvt_pk_bf16_f32 v37, v44, v45
	global_store_dwordx4 v[46:47], v[34:37], off
	s_nop 1
	v_add_f32_e32 v34, 1.0, v38
	v_add_f32_e32 v35, 1.0, v39
	v_rcp_f32_e32 v34, v34
	v_rcp_f32_e32 v35, v35
	v_add_u32_e32 v36, 0xa0, v146
	v_mad_i64_i32 v[36:37], s[26:27], v36, s2, v[140:141]
	v_pk_mul_f32 v[30:31], v[30:31], v[34:35]
	v_mul_f32_e32 v34, 0xbfb8aa3b, v32
	v_mul_f32_e32 v35, 0xbfb8aa3b, v33
	v_exp_f32_e32 v34, v34
	v_exp_f32_e32 v35, v35
	v_pk_mul_f32 v[22:23], v[30:31], v[22:23]
	v_add_f32_e32 v30, 1.0, v34
	v_add_f32_e32 v31, 1.0, v35
	v_mul_f32_e32 v34, 0xbfb8aa3b, v26
	v_mul_f32_e32 v35, 0xbfb8aa3b, v27
	v_rcp_f32_e32 v30, v30
	v_rcp_f32_e32 v31, v31
	v_exp_f32_e32 v34, v34
	v_exp_f32_e32 v35, v35
	v_pk_mul_f32 v[30:31], v[32:33], v[30:31]
	v_add_f32_e32 v32, 1.0, v34
	v_add_f32_e32 v33, 1.0, v35
	v_mul_f32_e32 v34, 0xbfb8aa3b, v28
	v_mul_f32_e32 v35, 0xbfb8aa3b, v29
	v_exp_f32_e32 v34, v34
	v_exp_f32_e32 v35, v35
	v_rcp_f32_e32 v32, v32
	v_rcp_f32_e32 v33, v33
	v_add_f32_e32 v34, 1.0, v34
	v_add_f32_e32 v35, 1.0, v35
	v_rcp_f32_e32 v34, v34
	v_rcp_f32_e32 v35, v35
	v_pk_mul_f32 v[26:27], v[26:27], v[32:33]
	v_pk_mul_f32 v[24:25], v[30:31], v[24:25]
	v_pk_mul_f32 v[26:27], v[26:27], v[18:19]
	v_pk_mul_f32 v[18:19], v[28:29], v[34:35]
	v_lshl_add_u64 v[30:31], v[36:37], 0, v[114:115]
	v_pk_mul_f32 v[28:29], v[18:19], v[20:21]
	v_cvt_pk_bf16_f32 v18, v22, v23
	v_mul_f32_e32 v22, 0xbfb8aa3b, v12
	v_mul_f32_e32 v23, 0xbfb8aa3b, v13
	v_exp_f32_e32 v22, v22
	v_exp_f32_e32 v23, v23
	v_cvt_pk_bf16_f32 v19, v24, v25
	v_cvt_pk_bf16_f32 v20, v26, v27
	v_cvt_pk_bf16_f32 v21, v28, v29
	global_store_dwordx4 v[30:31], v[18:21], off
	s_nop 1
	v_add_f32_e32 v18, 1.0, v22
	v_add_f32_e32 v19, 1.0, v23
	v_rcp_f32_e32 v18, v18
	v_rcp_f32_e32 v19, v19
	v_add_u32_e32 v20, 0xb0, v146
	v_mad_i64_i32 v[20:21], s[26:27], v20, s2, v[140:141]
	v_pk_mul_f32 v[12:13], v[12:13], v[18:19]
	v_mul_f32_e32 v18, 0xbfb8aa3b, v14
	v_mul_f32_e32 v19, 0xbfb8aa3b, v15
	v_exp_f32_e32 v18, v18
	v_exp_f32_e32 v19, v19
	v_pk_mul_f32 v[4:5], v[12:13], v[4:5]
	v_add_f32_e32 v12, 1.0, v18
	v_add_f32_e32 v13, 1.0, v19
	v_mul_f32_e32 v18, 0xbfb8aa3b, v8
	v_mul_f32_e32 v19, 0xbfb8aa3b, v9
	v_rcp_f32_e32 v12, v12
	v_rcp_f32_e32 v13, v13
	v_exp_f32_e32 v18, v18
	v_exp_f32_e32 v19, v19
	v_pk_mul_f32 v[12:13], v[14:15], v[12:13]
	v_add_f32_e32 v14, 1.0, v18
	v_add_f32_e32 v15, 1.0, v19
	v_mul_f32_e32 v18, 0xbfb8aa3b, v10
	v_mul_f32_e32 v19, 0xbfb8aa3b, v11
	v_exp_f32_e32 v18, v18
	v_exp_f32_e32 v19, v19
	v_rcp_f32_e32 v14, v14
	v_rcp_f32_e32 v15, v15
	v_add_f32_e32 v18, 1.0, v18
	v_add_f32_e32 v19, 1.0, v19
	v_rcp_f32_e32 v18, v18
	v_rcp_f32_e32 v19, v19
	v_pk_mul_f32 v[8:9], v[8:9], v[14:15]
	v_pk_mul_f32 v[6:7], v[12:13], v[6:7]
	v_pk_mul_f32 v[8:9], v[8:9], v[0:1]
	v_pk_mul_f32 v[0:1], v[10:11], v[18:19]
	v_lshl_add_u64 v[12:13], v[20:21], 0, v[114:115]
	v_pk_mul_f32 v[10:11], v[0:1], v[2:3]
	v_cvt_pk_bf16_f32 v0, v4, v5
	v_cvt_pk_bf16_f32 v1, v6, v7
	v_cvt_pk_bf16_f32 v2, v8, v9
	v_cvt_pk_bf16_f32 v3, v10, v11
	global_store_dwordx4 v[12:13], v[0:3], off
	s_cbranch_vccnz .LBB0_697
	s_andn2_b64 vcc, exec, s[0:1]
	s_cbranch_vccnz .LBB0_696
	s_barrier
	s_branch .LBB0_696
